# stack: merge sigmoid via v_rcp_f32, prep w_in transpose loads issued 16-deep, qkv kv-loop block order reversed for balance (on top of scan rewrite)
# speedup vs baseline: 1.0257x; 1.0022x over previous
; DI void do_transpose(const float* __restrict__ src, int K, int N, u16* __restrict__ dst, const float* __restrict__ ksc, int perm, int tile, float* tl) {
;     ...
;   __syncthreads();
; #pragma unroll 4
;   for (int i = 0; i < 16; ++i) {
;     const int kk = i * 4 + (tid >> 6), nn = tid & 63;
;     float v = 0.f;
;     if (n0 + nn < N) v = src[(size_t)(k0 + kk) * N + n0 + nn];
;     if (ksc) v *= ksc[k0 + kk];
;     tl[kk * 65 + nn] = v;
;   }
.LBB0_279:
	v_mov_b32_e32 v16, 0
	v_mov_b32_e32 v17, 0
	v_mov_b32_e32 v18, 0
	v_mov_b32_e32 v19, 0
	v_mov_b32_e32 v20, 0
	v_mov_b32_e32 v21, 0
	v_mov_b32_e32 v22, 0
	v_mov_b32_e32 v23, 0
	v_mov_b32_e32 v24, 0
	v_mov_b32_e32 v25, 0
	v_mov_b32_e32 v26, 0
	v_mov_b32_e32 v27, 0
	v_mov_b32_e32 v28, 0
	v_mov_b32_e32 v29, 0
	v_mov_b32_e32 v30, 0
	v_mov_b32_e32 v31, 0
	s_and_saveexec_b64 s[6:7], vcc
	s_cbranch_execz .Lwin_ld_done
	v_mad_i64_i32 v[10:11], s[58:59], v1, s93, v[4:5]
	global_load_dword v16, v[10:11], off
	v_add_u32_e32 v7, 4, v1
	v_mad_i64_i32 v[10:11], s[58:59], v7, s93, v[4:5]
	global_load_dword v17, v[10:11], off
	v_add_u32_e32 v7, 8, v1
	v_mad_i64_i32 v[10:11], s[58:59], v7, s93, v[4:5]
	global_load_dword v18, v[10:11], off
	v_add_u32_e32 v7, 12, v1
	v_mad_i64_i32 v[10:11], s[58:59], v7, s93, v[4:5]
	global_load_dword v19, v[10:11], off
	v_add_u32_e32 v7, 16, v1
	v_mad_i64_i32 v[10:11], s[58:59], v7, s93, v[4:5]
	global_load_dword v20, v[10:11], off
	v_add_u32_e32 v7, 20, v1
	v_mad_i64_i32 v[10:11], s[58:59], v7, s93, v[4:5]
	global_load_dword v21, v[10:11], off
	v_add_u32_e32 v7, 24, v1
	v_mad_i64_i32 v[10:11], s[58:59], v7, s93, v[4:5]
	global_load_dword v22, v[10:11], off
	v_add_u32_e32 v7, 28, v1
	v_mad_i64_i32 v[10:11], s[58:59], v7, s93, v[4:5]
	global_load_dword v23, v[10:11], off
	v_add_u32_e32 v7, 32, v1
	v_mad_i64_i32 v[10:11], s[58:59], v7, s93, v[4:5]
	global_load_dword v24, v[10:11], off
	v_add_u32_e32 v7, 36, v1
	v_mad_i64_i32 v[10:11], s[58:59], v7, s93, v[4:5]
	global_load_dword v25, v[10:11], off
	v_add_u32_e32 v7, 40, v1
	v_mad_i64_i32 v[10:11], s[58:59], v7, s93, v[4:5]
	global_load_dword v26, v[10:11], off
	v_add_u32_e32 v7, 44, v1
	v_mad_i64_i32 v[10:11], s[58:59], v7, s93, v[4:5]
	global_load_dword v27, v[10:11], off
	v_add_u32_e32 v7, 48, v1
	v_mad_i64_i32 v[10:11], s[58:59], v7, s93, v[4:5]
	global_load_dword v28, v[10:11], off
	v_add_u32_e32 v7, 52, v1
	v_mad_i64_i32 v[10:11], s[58:59], v7, s93, v[4:5]
	global_load_dword v29, v[10:11], off
	v_add_u32_e32 v7, 56, v1
	v_mad_i64_i32 v[10:11], s[58:59], v7, s93, v[4:5]
	global_load_dword v30, v[10:11], off
	v_add_u32_e32 v7, 60, v1
	v_mad_i64_i32 v[10:11], s[58:59], v7, s93, v[4:5]
	global_load_dword v31, v[10:11], off
.Lwin_ld_done:
	s_or_b64 exec, exec, s[6:7]
	s_waitcnt vmcnt(0)
	ds_write_b32 v6, v16
	ds_write_b32 v6, v17 offset:1040
	ds_write_b32 v6, v18 offset:2080
	ds_write_b32 v6, v19 offset:3120
	ds_write_b32 v6, v20 offset:4160
	ds_write_b32 v6, v21 offset:5200
	ds_write_b32 v6, v22 offset:6240
	ds_write_b32 v6, v23 offset:7280
	ds_write_b32 v6, v24 offset:8320
	ds_write_b32 v6, v25 offset:9360
	ds_write_b32 v6, v26 offset:10400
	ds_write_b32 v6, v27 offset:11440
	ds_write_b32 v6, v28 offset:12480
	ds_write_b32 v6, v29 offset:13520
	ds_write_b32 v6, v30 offset:14560
	ds_write_b32 v6, v31 offset:15600

; DI unsigned pack2(float a, float b) { float2_t v = {a, b}; bf16x2_t r = __builtin_convertvector(v, bf16x2_t); return __builtin_bit_cast(unsigned, r); }
; DI float sigmoidf_(float x) { return 1.f / (1.f + __expf(-x)); }
; template <int MI, int NI>
; DI void gemm256(f32x4 (&acc)[MI][NI], const u16* __restrict__ A, int lda, const u16* __restrict__ Bt, int ldb, int K, int m0, int n0, char* smem) {
;     ...
;   for (int kt = 0; kt < nk; ++kt) {
;     if (kt + 1 < nk) asm volatile("s_waitcnt vmcnt(%0) lgkmcnt(0)" :: "n"(LPS) : "memory");
;     else asm volatile("s_waitcnt vmcnt(0) lgkmcnt(0)" ::: "memory");
;     __builtin_amdgcn_s_barrier();
;     __builtin_amdgcn_s_setprio(1);
;     const char* sb = smem + st * STAGE + foff;
;     bf16x8 af[MI], bfr[NI];
; #pragma unroll
;     for (int mi = 0; mi < MI; ++mi) af[mi] = *(const bf16x8*)(sb + (wr * MI + mi) * 1024);
; #pragma unroll
;     for (int ni = 0; ni < NI; ++ni) bfr[ni] = *(const bf16x8*)(sb + ABYTES + (wc * NI + ni) * 1024);
; DI void phase_merge(const Params& p, int l, int Mout, char* smem) {
;     ...
; #pragma unroll
;         for (int mi = 0; mi < 4; ++mi)
; #pragma unroll
;           for (int ni = 0; ni < 4; ++ni) {
;             gpk[mi][ni][0] = pack2(sigmoidf_(ag[mi][ni][0]), sigmoidf_(ag[mi][ni][1]));
;             gpk[mi][ni][1] = pack2(sigmoidf_(ag[mi][ni][2]), sigmoidf_(ag[mi][ni][3]));
;           }
.LBB0_478:
	v_mul_f32_e32 v126, 0xbfb8aa3b, v126
	v_mul_f32_e32 v127, 0xbfb8aa3b, v127
	v_exp_f32_e32 v126, v126
	v_exp_f32_e32 v127, v127
	v_mul_f32_e32 v122, 0xbfb8aa3b, v122
	v_mul_f32_e32 v123, 0xbfb8aa3b, v123
	v_exp_f32_e32 v122, v122
	v_pk_add_f32 v[126:127], v[126:127], 1.0 op_sel_hi:[1,0]
	v_exp_f32_e32 v123, v123
	s_nop 0
	v_pk_add_f32 v[122:123], v[122:123], 1.0 op_sel_hi:[1,0]
	v_mul_f32_e32 v118, 0xbfb8aa3b, v118
	v_mul_f32_e32 v119, 0xbfb8aa3b, v119
	v_rcp_f32_e32 v127, v127
	v_exp_f32_e32 v118, v118
	v_exp_f32_e32 v119, v119
	v_mul_f32_e32 v114, 0xbfb8aa3b, v114
	v_rcp_f32_e32 v126, v126
	s_nop 0
	v_cvt_pk_bf16_f32 v126, v126, v127
	v_mul_f32_e32 v127, 0xbfb8aa3b, v128
	v_exp_f32_e32 v128, v127
	v_mul_f32_e32 v127, 0xbfb8aa3b, v129
	v_exp_f32_e32 v129, v127
	v_pk_add_f32 v[118:119], v[118:119], 1.0 op_sel_hi:[1,0]
	v_mul_f32_e32 v115, 0xbfb8aa3b, v115
	v_exp_f32_e32 v114, v114
	v_pk_add_f32 v[128:129], v[128:129], 1.0 op_sel_hi:[1,0]
	v_exp_f32_e32 v115, v115
	s_nop 0
	v_pk_add_f32 v[114:115], v[114:115], 1.0 op_sel_hi:[1,0]
	v_mul_f32_e32 v110, 0xbfb8aa3b, v110
	v_mul_f32_e32 v111, 0xbfb8aa3b, v111
	v_rcp_f32_e32 v127, v129
	v_exp_f32_e32 v110, v110
	v_exp_f32_e32 v111, v111
	v_mul_f32_e32 v106, 0xbfb8aa3b, v106
	v_rcp_f32_e32 v128, v128
	s_nop 0
	v_cvt_pk_bf16_f32 v127, v128, v127
	v_pk_add_f32 v[110:111], v[110:111], 1.0 op_sel_hi:[1,0]
	v_mul_f32_e32 v107, 0xbfb8aa3b, v107
	v_exp_f32_e32 v106, v106
	v_rcp_f32_e32 v123, v123
	v_exp_f32_e32 v107, v107
	v_mul_f32_e32 v102, 0xbfb8aa3b, v102
	v_mul_f32_e32 v103, 0xbfb8aa3b, v103
	v_rcp_f32_e32 v122, v122
	s_nop 0
	v_cvt_pk_bf16_f32 v122, v122, v123
	v_mul_f32_e32 v123, 0xbfb8aa3b, v124
	v_exp_f32_e32 v124, v123
	v_mul_f32_e32 v123, 0xbfb8aa3b, v125
	v_exp_f32_e32 v125, v123
	v_pk_add_f32 v[106:107], v[106:107], 1.0 op_sel_hi:[1,0]
	v_exp_f32_e32 v102, v102
	v_exp_f32_e32 v103, v103
	v_pk_add_f32 v[124:125], v[124:125], 1.0 op_sel_hi:[1,0]
	v_mul_f32_e32 v98, 0xbfb8aa3b, v98
	v_pk_add_f32 v[102:103], v[102:103], 1.0 op_sel_hi:[1,0]
	v_mul_f32_e32 v99, 0xbfb8aa3b, v99
	v_exp_f32_e32 v98, v98
	v_rcp_f32_e32 v123, v125
	v_exp_f32_e32 v99, v99
	v_mul_f32_e32 v94, 0xbfb8aa3b, v94
	v_mul_f32_e32 v95, 0xbfb8aa3b, v95
	v_rcp_f32_e32 v124, v124
	s_nop 0
	v_cvt_pk_bf16_f32 v123, v124, v123
	v_pk_add_f32 v[98:99], v[98:99], 1.0 op_sel_hi:[1,0]
	v_exp_f32_e32 v94, v94
	v_exp_f32_e32 v95, v95
	v_rcp_f32_e32 v119, v119
	v_pk_add_f32 v[94:95], v[94:95], 1.0 op_sel_hi:[1,0]
	v_mul_f32_e32 v90, 0xbfb8aa3b, v90
	v_mul_f32_e32 v91, 0xbfb8aa3b, v91
	v_rcp_f32_e32 v118, v118
	s_nop 0
	v_cvt_pk_bf16_f32 v118, v118, v119
	v_mul_f32_e32 v119, 0xbfb8aa3b, v120
	v_exp_f32_e32 v120, v119
	v_mul_f32_e32 v119, 0xbfb8aa3b, v121
	v_exp_f32_e32 v121, v119
	v_exp_f32_e32 v90, v90
	v_exp_f32_e32 v91, v91
	v_mul_f32_e32 v86, 0xbfb8aa3b, v86
	v_pk_add_f32 v[120:121], v[120:121], 1.0 op_sel_hi:[1,0]
	v_mul_f32_e32 v87, 0xbfb8aa3b, v87
	v_pk_add_f32 v[90:91], v[90:91], 1.0 op_sel_hi:[1,0]
	v_exp_f32_e32 v86, v86
	v_exp_f32_e32 v87, v87
	v_rcp_f32_e32 v119, v121
	v_pk_add_f32 v[86:87], v[86:87], 1.0 op_sel_hi:[1,0]
	v_mul_f32_e32 v82, 0xbfb8aa3b, v82
	v_mul_f32_e32 v83, 0xbfb8aa3b, v83
	v_rcp_f32_e32 v120, v120
	s_nop 0
	v_cvt_pk_bf16_f32 v119, v120, v119
	v_exp_f32_e32 v82, v82
	v_exp_f32_e32 v83, v83
	v_mul_f32_e32 v78, 0xbfb8aa3b, v78
	v_rcp_f32_e32 v115, v115
	v_pk_add_f32 v[82:83], v[82:83], 1.0 op_sel_hi:[1,0]
	v_mul_f32_e32 v79, 0xbfb8aa3b, v79
	v_exp_f32_e32 v78, v78
	v_rcp_f32_e32 v114, v114
	s_nop 0
	v_cvt_pk_bf16_f32 v114, v114, v115
	v_mul_f32_e32 v115, 0xbfb8aa3b, v116
	v_exp_f32_e32 v116, v115
	v_mul_f32_e32 v115, 0xbfb8aa3b, v117
	v_exp_f32_e32 v117, v115
	v_exp_f32_e32 v79, v79
	v_mul_f32_e32 v74, 0xbfb8aa3b, v74
	v_mul_f32_e32 v75, 0xbfb8aa3b, v75
	v_pk_add_f32 v[116:117], v[116:117], 1.0 op_sel_hi:[1,0]
	v_pk_add_f32 v[78:79], v[78:79], 1.0 op_sel_hi:[1,0]
	v_exp_f32_e32 v74, v74
	v_exp_f32_e32 v75, v75
	v_mul_f32_e32 v70, 0xbfb8aa3b, v70
	v_rcp_f32_e32 v115, v117
	v_pk_add_f32 v[74:75], v[74:75], 1.0 op_sel_hi:[1,0]
	v_mul_f32_e32 v71, 0xbfb8aa3b, v71
	v_exp_f32_e32 v70, v70
	v_rcp_f32_e32 v116, v116
	s_nop 0
	v_cvt_pk_bf16_f32 v115, v116, v115
	v_exp_f32_e32 v71, v71
	v_mul_f32_e32 v66, 0xbfb8aa3b, v66
	v_mul_f32_e32 v67, 0xbfb8aa3b, v67
	v_rcp_f32_e32 v111, v111
	v_pk_add_f32 v[70:71], v[70:71], 1.0 op_sel_hi:[1,0]
	v_exp_f32_e32 v66, v66
	v_exp_f32_e32 v67, v67
	v_rcp_f32_e32 v110, v110
	s_nop 0
	v_cvt_pk_bf16_f32 v110, v110, v111
	v_mul_f32_e32 v111, 0xbfb8aa3b, v112
	v_exp_f32_e32 v112, v111
	v_mul_f32_e32 v111, 0xbfb8aa3b, v113
	v_exp_f32_e32 v113, v111
	v_pk_add_f32 v[66:67], v[66:67], 1.0 op_sel_hi:[1,0]
	s_waitcnt vmcnt(0) lgkmcnt(0)
	s_barrier
; DI unsigned pack2(float a, float b) { float2_t v = {a, b}; bf16x2_t r = __builtin_convertvector(v, bf16x2_t); return __builtin_bit_cast(unsigned, r); }
; DI float sigmoidf_(float x) { return 1.f / (1.f + __expf(-x)); }
; template <int MI, int NI>
; DI void gemm256(f32x4 (&acc)[MI][NI], const u16* __restrict__ A, int lda, const u16* __restrict__ Bt, int ldb, int K, int m0, int n0, char* smem) {
;     ...
;   for (int kt = 0; kt < nk; ++kt) {
;     if (kt + 1 < nk) asm volatile("s_waitcnt vmcnt(%0) lgkmcnt(0)" :: "n"(LPS) : "memory");
;     else asm volatile("s_waitcnt vmcnt(0) lgkmcnt(0)" ::: "memory");
;     __builtin_amdgcn_s_barrier();
;     __builtin_amdgcn_s_setprio(1);
;     const char* sb = smem + st * STAGE + foff;
;     bf16x8 af[MI], bfr[NI];
; #pragma unroll
;     for (int mi = 0; mi < MI; ++mi) af[mi] = *(const bf16x8*)(sb + (wr * MI + mi) * 1024);
; #pragma unroll
;     for (int ni = 0; ni < NI; ++ni) bfr[ni] = *(const bf16x8*)(sb + ABYTES + (wc * NI + ni) * 1024);
;     __builtin_amdgcn_sched_barrier(0x0);
;     if (kt + 2 < nk) { const int s2 = st >= 1 ? st - 1 : 2; G256_ISSUE(s2, (kt + 2) * 32); }
;     __builtin_amdgcn_s_setprio(0);
; #pragma unroll
;     for (int mi = 0; mi < MI; ++mi)
; #pragma unroll
;       for (int ni = 0; ni < NI; ++ni)
;         acc[mi][ni] = __builtin_amdgcn_mfma_f32_16x16x32_bf16(bfr[ni], af[mi], acc[mi][ni], 0, 0, 0);
; DI void phase_merge(const Params& p, int l, int Mout, char* smem) {
;     ...
; #pragma unroll
;         for (int mi = 0; mi < 4; ++mi)
; #pragma unroll
;           for (int ni = 0; ni < 4; ++ni) {
;             gpk[mi][ni][0] = pack2(sigmoidf_(ag[mi][ni][0]), sigmoidf_(ag[mi][ni][1]));
;             gpk[mi][ni][1] = pack2(sigmoidf_(ag[mi][ni][2]), sigmoidf_(ag[mi][ni][3]));
;           }
	v_pk_add_f32 v[112:113], v[112:113], 1.0 op_sel_hi:[1,0]
	s_nop 0
	s_nop 0
	v_rcp_f32_e32 v111, v113
	s_nop 0
	v_rcp_f32_e32 v112, v112
	s_nop 0
	v_cvt_pk_bf16_f32 v111, v112, v111
	s_nop 0
	v_rcp_f32_e32 v107, v107
	s_nop 0
	v_rcp_f32_e32 v106, v106
	s_nop 0
	v_cvt_pk_bf16_f32 v106, v106, v107
	v_mul_f32_e32 v107, 0xbfb8aa3b, v108
	v_exp_f32_e32 v108, v107
	v_mul_f32_e32 v107, 0xbfb8aa3b, v109
	v_exp_f32_e32 v109, v107
	s_nop 0
	v_pk_add_f32 v[108:109], v[108:109], 1.0 op_sel_hi:[1,0]
	s_nop 0
	s_nop 0
	v_rcp_f32_e32 v107, v109
	s_nop 0
	v_rcp_f32_e32 v108, v108
	s_nop 0
	v_cvt_pk_bf16_f32 v107, v108, v107
	s_nop 0
	v_rcp_f32_e32 v103, v103
	s_nop 0
	v_rcp_f32_e32 v102, v102
	s_nop 0
	v_cvt_pk_bf16_f32 v102, v102, v103
	v_mul_f32_e32 v103, 0xbfb8aa3b, v104
	v_exp_f32_e32 v104, v103
	v_mul_f32_e32 v103, 0xbfb8aa3b, v105
	v_exp_f32_e32 v105, v103
	s_nop 0
	v_pk_add_f32 v[104:105], v[104:105], 1.0 op_sel_hi:[1,0]
	s_nop 0
	s_nop 0
	v_rcp_f32_e32 v103, v105
	s_nop 0
	v_rcp_f32_e32 v104, v104
	s_nop 0
	v_cvt_pk_bf16_f32 v103, v104, v103
	s_nop 0
	v_rcp_f32_e32 v99, v99
	s_nop 0
	v_rcp_f32_e32 v98, v98
	s_nop 0
	v_cvt_pk_bf16_f32 v98, v98, v99
	v_mul_f32_e32 v99, 0xbfb8aa3b, v100
	v_exp_f32_e32 v100, v99
	v_mul_f32_e32 v99, 0xbfb8aa3b, v101
	v_exp_f32_e32 v101, v99
	s_nop 0
	v_pk_add_f32 v[100:101], v[100:101], 1.0 op_sel_hi:[1,0]
	s_nop 0
	s_nop 0
	v_rcp_f32_e32 v99, v101
	s_nop 0
	v_rcp_f32_e32 v100, v100
	s_nop 0
	v_cvt_pk_bf16_f32 v99, v100, v99
	s_nop 0
	v_rcp_f32_e32 v95, v95
	s_nop 0
	v_rcp_f32_e32 v94, v94
	s_nop 0
	v_cvt_pk_bf16_f32 v94, v94, v95
	v_mul_f32_e32 v95, 0xbfb8aa3b, v96
	v_exp_f32_e32 v96, v95
	v_mul_f32_e32 v95, 0xbfb8aa3b, v97
	v_exp_f32_e32 v97, v95
	s_nop 0
	v_pk_add_f32 v[96:97], v[96:97], 1.0 op_sel_hi:[1,0]
	s_nop 0
	s_nop 0
	v_rcp_f32_e32 v95, v97
	s_nop 0
	v_rcp_f32_e32 v96, v96
	s_nop 0
	v_cvt_pk_bf16_f32 v95, v96, v95
	s_nop 0
	v_rcp_f32_e32 v91, v91
	s_nop 0
	v_rcp_f32_e32 v90, v90
	s_nop 0
	v_cvt_pk_bf16_f32 v90, v90, v91
	v_mul_f32_e32 v91, 0xbfb8aa3b, v92
	v_exp_f32_e32 v92, v91
	v_mul_f32_e32 v91, 0xbfb8aa3b, v93
	v_exp_f32_e32 v93, v91
	s_nop 0
	v_pk_add_f32 v[92:93], v[92:93], 1.0 op_sel_hi:[1,0]
	s_nop 0
	s_nop 0
	v_rcp_f32_e32 v91, v93
	s_nop 0
	v_rcp_f32_e32 v92, v92
	s_nop 0
	v_cvt_pk_bf16_f32 v91, v92, v91
	s_nop 0
	v_rcp_f32_e32 v87, v87
	s_nop 0
	v_rcp_f32_e32 v86, v86
	s_nop 0
	v_cvt_pk_bf16_f32 v86, v86, v87
	v_mul_f32_e32 v87, 0xbfb8aa3b, v88
	v_exp_f32_e32 v88, v87
	v_mul_f32_e32 v87, 0xbfb8aa3b, v89
	v_exp_f32_e32 v89, v87
	s_nop 0
	v_pk_add_f32 v[88:89], v[88:89], 1.0 op_sel_hi:[1,0]
	s_nop 0
	s_nop 0
	v_rcp_f32_e32 v87, v89
	s_nop 0
	v_rcp_f32_e32 v88, v88
	s_nop 0
	v_cvt_pk_bf16_f32 v87, v88, v87
	s_nop 0
	v_rcp_f32_e32 v83, v83
	s_nop 0
	v_rcp_f32_e32 v82, v82
	s_nop 0
	v_cvt_pk_bf16_f32 v82, v82, v83
	v_mul_f32_e32 v83, 0xbfb8aa3b, v84
	v_exp_f32_e32 v84, v83
	v_mul_f32_e32 v83, 0xbfb8aa3b, v85
	v_exp_f32_e32 v85, v83
	s_nop 0
	v_pk_add_f32 v[84:85], v[84:85], 1.0 op_sel_hi:[1,0]
	s_nop 0
	s_nop 0
	v_rcp_f32_e32 v83, v85
	s_nop 0
	v_rcp_f32_e32 v84, v84
	s_nop 0
	v_cvt_pk_bf16_f32 v83, v84, v83
	s_nop 0
	v_rcp_f32_e32 v79, v79
	s_nop 0
	v_rcp_f32_e32 v78, v78
	s_nop 0
	v_cvt_pk_bf16_f32 v78, v78, v79
	v_mul_f32_e32 v79, 0xbfb8aa3b, v80
	v_exp_f32_e32 v80, v79
	v_mul_f32_e32 v79, 0xbfb8aa3b, v81
	v_exp_f32_e32 v81, v79
	s_nop 0
	v_pk_add_f32 v[80:81], v[80:81], 1.0 op_sel_hi:[1,0]
	s_nop 0
	s_nop 0
	v_rcp_f32_e32 v79, v81
	s_nop 0
	v_rcp_f32_e32 v80, v80
	s_nop 0
	v_cvt_pk_bf16_f32 v79, v80, v79
	s_nop 0
	v_rcp_f32_e32 v75, v75
	s_nop 0
	v_rcp_f32_e32 v74, v74
	s_nop 0
	v_cvt_pk_bf16_f32 v74, v74, v75
	v_mul_f32_e32 v75, 0xbfb8aa3b, v76
	v_exp_f32_e32 v76, v75
	v_mul_f32_e32 v75, 0xbfb8aa3b, v77
	v_exp_f32_e32 v77, v75
	s_nop 0
	v_pk_add_f32 v[76:77], v[76:77], 1.0 op_sel_hi:[1,0]
	s_nop 0
	s_nop 0
	v_rcp_f32_e32 v75, v77
	s_nop 0
	v_rcp_f32_e32 v76, v76
	s_nop 0
	v_cvt_pk_bf16_f32 v75, v76, v75
	s_nop 0
	v_rcp_f32_e32 v71, v71
	s_nop 0
	v_rcp_f32_e32 v70, v70
	s_nop 0
	v_cvt_pk_bf16_f32 v70, v70, v71
	v_mul_f32_e32 v71, 0xbfb8aa3b, v72
	v_exp_f32_e32 v72, v71
	v_mul_f32_e32 v71, 0xbfb8aa3b, v73
	v_exp_f32_e32 v73, v71
	s_nop 0
	v_pk_add_f32 v[72:73], v[72:73], 1.0 op_sel_hi:[1,0]
	s_nop 0
	s_nop 0
	v_rcp_f32_e32 v71, v73
	s_nop 0
	v_rcp_f32_e32 v72, v72
	s_nop 0
	v_cvt_pk_bf16_f32 v71, v72, v71
	s_nop 0
	v_rcp_f32_e32 v67, v67
	s_nop 0
	v_rcp_f32_e32 v66, v66
	s_nop 0
	v_cvt_pk_bf16_f32 v76, v66, v67
	v_mul_f32_e32 v66, 0xbfb8aa3b, v68
	v_mul_f32_e32 v67, 0xbfb8aa3b, v69
	v_exp_f32_e32 v66, v66
	v_exp_f32_e32 v67, v67
	s_nop 0
	v_pk_add_f32 v[66:67], v[66:67], 1.0 op_sel_hi:[1,0]
	s_nop 0
	s_nop 0
	v_rcp_f32_e32 v67, v67
	s_nop 0
	v_rcp_f32_e32 v66, v66
	s_nop 0
	v_cvt_pk_bf16_f32 v77, v66, v67
	s_setprio 1
	v_lshl_or_b32 v72, s15, 14, v248
	v_add_u32_e32 v73, v72, v249
	v_add_u32_e32 v0, v72, v0
	s_waitcnt vmcnt(0)
	ds_read_b128 v[66:69], v73
	ds_read_b128 v[128:131], v73 offset:1024
	ds_read_b128 v[132:135], v73 offset:2048
	ds_read_b128 v[136:139], v73 offset:3072
	ds_read_b128 v[140:143], v0 offset:8192
	ds_read_b128 v[144:147], v0 offset:9216
	ds_read_b128 v[148:151], v0 offset:10240
	ds_read_b128 v[152:155], v0 offset:11264
	s_setprio 0
	s_waitcnt lgkmcnt(3)
	v_mfma_f32_16x16x32_bf16 v[62:65], v[140:143], v[66:69], v[62:65]
	v_lshlrev_b32_e32 v72, 16, v126
	v_and_b32_e32 v73, 0xffff0000, v126
	s_waitcnt lgkmcnt(0)
	s_waitcnt lgkmcnt(2)
	v_mfma_f32_16x16x32_bf16 v[58:61], v[144:147], v[66:69], v[58:61]
	s_barrier
; DI float bflo(unsigned u) { return __uint_as_float(u << 16); }
; DI float bfhi(unsigned u) { return __uint_as_float(u & 0xffff0000u); }
; template <int MI, int NI>
; DI void gemm256(f32x4 (&acc)[MI][NI], const u16* __restrict__ A, int lda, const u16* __restrict__ Bt, int ldb, int K, int m0, int n0, char* smem) {
;     ...
;         acc[mi][ni] = __builtin_amdgcn_mfma_f32_16x16x32_bf16(bfr[ni], af[mi], acc[mi][ni], 0, 0, 0);
; DI void phase_merge(const Params& p, int l, int Mout, char* smem) {
;     ...
;       f32x4 ab[4][4]; zero_accm<4, 4>(ab);
;       {
;         const int Kb = br == 1 ? 512 : 256;
;         const u16* Ab = br == 0 ? opool : br == 1 ? omla : orw;
;         const u16* Wb = (const u16*)(wl + (br == 0 ? WO_BRP : br == 1 ? WO_BRM : WO_BRR));
;         gemm256<4, 4>(ab, Ab, Kb, Wb, Kb, Kb, m0, n0, smem);
;       }
; #pragma unroll
;       for (int mi = 0; mi < 4; ++mi)
; #pragma unroll
;         for (int ni = 0; ni < 4; ++ni) {
;           msum[mi][ni][0] += bflo(gpk[mi][ni][0]) * ab[mi][ni][0];
;           msum[mi][ni][1] += bfhi(gpk[mi][ni][0]) * ab[mi][ni][1];
;           msum[mi][ni][2] += bflo(gpk[mi][ni][1]) * ab[mi][ni][2];
;           msum[mi][ni][3] += bfhi(gpk[mi][ni][1]) * ab[mi][ni][3];
;         }
;       __builtin_amdgcn_sched_barrier(0);
;     }
	s_nop 2
	v_pk_fma_f32 v[220:221], v[62:63], v[72:73], v[220:221]
	v_lshlrev_b32_e32 v62, 16, v127
	v_and_b32_e32 v63, 0xffff0000, v127
	s_waitcnt lgkmcnt(1)
	v_mfma_f32_16x16x32_bf16 v[54:57], v[148:151], v[66:69], v[54:57]
	v_fma_f32 v222, v64, v62, v222
	v_fma_f32 v223, v65, v63, v223
	v_lshlrev_b32_e32 v62, 16, v122
	v_and_b32_e32 v63, 0xffff0000, v122
	v_pk_fma_f32 v[208:209], v[58:59], v[62:63], v[208:209]
	s_waitcnt lgkmcnt(0)
	v_mfma_f32_16x16x32_bf16 v[50:53], v[152:155], v[66:69], v[50:53]
	v_lshlrev_b32_e32 v58, 16, v123
	v_and_b32_e32 v59, 0xffff0000, v123
	v_pk_fma_f32 v[210:211], v[60:61], v[58:59], v[210:211]
	v_lshlrev_b32_e32 v58, 16, v118
	v_and_b32_e32 v59, 0xffff0000, v118
	v_mfma_f32_16x16x32_bf16 v[46:49], v[140:143], v[128:131], v[46:49]
	v_fma_f32 v196, v54, v58, v196
	v_fma_f32 v197, v55, v59, v197
	v_lshlrev_b32_e32 v54, 16, v119
	v_and_b32_e32 v55, 0xffff0000, v119
	v_pk_fma_f32 v[198:199], v[56:57], v[54:55], v[198:199]
	v_lshlrev_b32_e32 v54, 16, v114
	v_and_b32_e32 v55, 0xffff0000, v114
	v_mfma_f32_16x16x32_bf16 v[42:45], v[144:147], v[128:131], v[42:45]
	v_fma_f32 v186, v50, v54, v186
	v_fma_f32 v187, v51, v55, v187
	v_lshlrev_b32_e32 v50, 16, v115
	v_and_b32_e32 v51, 0xffff0000, v115
	v_pk_fma_f32 v[190:191], v[52:53], v[50:51], v[190:191]
	v_lshlrev_b32_e32 v50, 16, v110
	v_and_b32_e32 v51, 0xffff0000, v110
	v_mfma_f32_16x16x32_bf16 v[38:41], v[148:151], v[128:131], v[38:41]
	v_fma_f32 v224, v46, v50, v224
	v_fma_f32 v225, v47, v51, v225
	v_lshlrev_b32_e32 v46, 16, v111
	v_and_b32_e32 v47, 0xffff0000, v111
	v_pk_fma_f32 v[226:227], v[48:49], v[46:47], v[226:227]
	v_lshlrev_b32_e32 v46, 16, v106
	v_and_b32_e32 v47, 0xffff0000, v106
	v_mfma_f32_16x16x32_bf16 v[34:37], v[152:155], v[128:131], v[34:37]
	v_fma_f32 v216, v42, v46, v216
	v_fma_f32 v217, v43, v47, v217
	v_lshlrev_b32_e32 v42, 16, v107
	v_and_b32_e32 v43, 0xffff0000, v107
	v_pk_fma_f32 v[218:219], v[44:45], v[42:43], v[218:219]
	v_lshlrev_b32_e32 v42, 16, v102
	v_and_b32_e32 v43, 0xffff0000, v102
	v_mfma_f32_16x16x32_bf16 v[30:33], v[140:143], v[132:135], v[30:33]
	v_fma_f32 v212, v38, v42, v212
	v_fma_f32 v213, v39, v43, v213
	v_lshlrev_b32_e32 v38, 16, v103
	v_and_b32_e32 v39, 0xffff0000, v103
	v_pk_fma_f32 v[214:215], v[40:41], v[38:39], v[214:215]
	v_lshlrev_b32_e32 v38, 16, v98
	v_and_b32_e32 v39, 0xffff0000, v98
	v_mfma_f32_16x16x32_bf16 v[26:29], v[144:147], v[132:135], v[26:29]
	v_fma_f32 v202, v34, v38, v202
	v_fma_f32 v203, v35, v39, v203
	v_lshlrev_b32_e32 v34, 16, v99
	v_and_b32_e32 v35, 0xffff0000, v99
	v_pk_fma_f32 v[206:207], v[36:37], v[34:35], v[206:207]
	v_lshlrev_b32_e32 v34, 16, v94
	v_and_b32_e32 v35, 0xffff0000, v94
	v_mfma_f32_16x16x32_bf16 v[22:25], v[148:151], v[132:135], v[22:25]
	v_fma_f32 v184, v30, v34, v184
	v_fma_f32 v185, v31, v35, v185
	v_lshlrev_b32_e32 v30, 16, v95
	v_and_b32_e32 v31, 0xffff0000, v95
	v_pk_fma_f32 v[188:189], v[32:33], v[30:31], v[188:189]
	v_lshlrev_b32_e32 v30, 16, v90
	v_and_b32_e32 v31, 0xffff0000, v90
	v_mfma_f32_16x16x32_bf16 v[18:21], v[152:155], v[132:135], v[18:21]
	v_fma_f32 v176, v26, v30, v176
	v_fma_f32 v177, v27, v31, v177
	v_lshlrev_b32_e32 v26, 16, v91
	v_and_b32_e32 v27, 0xffff0000, v91
	v_pk_fma_f32 v[178:179], v[28:29], v[26:27], v[178:179]
	v_lshlrev_b32_e32 v26, 16, v86
	v_and_b32_e32 v27, 0xffff0000, v86
	v_mfma_f32_16x16x32_bf16 v[14:17], v[140:143], v[136:139], v[14:17]
	v_fma_f32 v168, v22, v26, v168
	v_fma_f32 v169, v23, v27, v169
	v_lshlrev_b32_e32 v22, 16, v87
	v_and_b32_e32 v23, 0xffff0000, v87
	v_pk_fma_f32 v[170:171], v[24:25], v[22:23], v[170:171]
	v_lshlrev_b32_e32 v22, 16, v82
	v_and_b32_e32 v23, 0xffff0000, v82
	v_mfma_f32_16x16x32_bf16 v[10:13], v[144:147], v[136:139], v[10:13]
	v_fma_f32 v164, v18, v22, v164
	v_fma_f32 v165, v19, v23, v165
	v_lshlrev_b32_e32 v18, 16, v83
	v_and_b32_e32 v19, 0xffff0000, v83
	v_pk_fma_f32 v[166:167], v[20:21], v[18:19], v[166:167]
	v_lshlrev_b32_e32 v18, 16, v78
	v_and_b32_e32 v19, 0xffff0000, v78
	v_mfma_f32_16x16x32_bf16 v[6:9], v[148:151], v[136:139], v[6:9]
	v_fma_f32 v200, v14, v18, v200
	v_fma_f32 v201, v15, v19, v201
	v_lshlrev_b32_e32 v14, 16, v79
	v_and_b32_e32 v15, 0xffff0000, v79
	v_pk_fma_f32 v[204:205], v[16:17], v[14:15], v[204:205]
	v_lshlrev_b32_e32 v14, 16, v74
	v_and_b32_e32 v15, 0xffff0000, v74
	v_mfma_f32_16x16x32_bf16 v[2:5], v[152:155], v[136:139], v[2:5]
	v_fma_f32 v192, v10, v14, v192
	v_fma_f32 v193, v11, v15, v193
	v_lshlrev_b32_e32 v10, 16, v75
	v_and_b32_e32 v11, 0xffff0000, v75
	v_pk_fma_f32 v[194:195], v[12:13], v[10:11], v[194:195]
	v_lshlrev_b32_e32 v10, 16, v70
	v_and_b32_e32 v11, 0xffff0000, v70
	v_pk_fma_f32 v[180:181], v[6:7], v[10:11], v[180:181]
	v_lshlrev_b32_e32 v6, 16, v71
	v_and_b32_e32 v7, 0xffff0000, v71
	v_pk_fma_f32 v[182:183], v[8:9], v[6:7], v[182:183]
	v_lshlrev_b32_e32 v6, 16, v76
	v_and_b32_e32 v7, 0xffff0000, v76
	v_pk_fma_f32 v[172:173], v[2:3], v[6:7], v[172:173]
	v_lshlrev_b32_e32 v2, 16, v77
	v_and_b32_e32 v3, 0xffff0000, v77
	v_pk_fma_f32 v[174:175], v[4:5], v[2:3], v[174:175]
	s_add_i32 s11, s11, 1
	s_add_u32 s4, s4, 0x200000
	s_addc_u32 s5, s5, 0
	s_cmp_eq_u32 s11, 3
	s_cbranch_scc1 .LBB0_473

; DI bool tile_map(int it, int NTM, int NTN, int blk, int nblk, int& tm, int& tn) {
;   const int xcd = blk & 7, local = blk >> 3, LB = nblk >> 3;
;   const int R = NTM >> 3;
;   const int s = it * LB + local;
;   if (s >= R * NTN) return false;
; DI void phase_qkv(const Params& p, int l, char* smem) {
;     ...
;   for (int it = 0;; ++it) {
;     int tm, tn;
;     if (!tile_map(it, NTM, 8, blk__, gridDim.x, tm, tn)) break;
.LBB0_712:
	s_sub_i32 s10, s39, s10
	s_add_i32 s10, s10, -1
	s_branch .LBB0_715
